# xcd barrier: waiting workgroups poll the release word less often (s_sleep 6)
# baseline (speedup 1.0000x reference)
; __device__ __forceinline__ unsigned xb_ld(unsigned* p)              { return __hip_atomic_load(p, __ATOMIC_RELAXED, __HIP_MEMORY_SCOPE_AGENT); }
; __device__ __forceinline__ unsigned xb_add(unsigned* p, unsigned v) { return __hip_atomic_fetch_add(p, v, __ATOMIC_RELAXED, __HIP_MEMORY_SCOPE_AGENT); }
; #define XB_SPIN(cond, bar) do { unsigned _sp = 0; while (cond) { __builtin_amdgcn_s_sleep(1); \
;     if ((++_sp & 255u) == 0u) { if (xb_ld(&(bar)[XB_TMO])) break; if (_sp > XB_SPIN_CAP) { atomicAdd(&(bar)[XB_TMO], 1u); break; } } } } while (0)
; __device__ __forceinline__ void xcd_barrier(const XcdBarrier& b) {
;     ...
;             else XB_SPIN(xb_ld(&bar[XB_TOPGEN]) == tg, bar);
;             __builtin_amdgcn_fence(__ATOMIC_ACQUIRE, "agent");
;             xb_add(&bar[XB_XGEN(b.x)], 1u);
;             asm volatile("s_waitcnt vmcnt(0)" ::: "memory");
;         } else {
;             XB_SPIN(xb_ld(&bar[XB_XGEN(b.x)]) == gen, bar);
.LBB0_131:
	s_and_b32 s24, s28, 0xff
	s_mov_b64 s[22:23], -1
	s_cmp_lg_u32 s24, 0
	s_mov_b64 s[26:27], -1
	s_sleep 6
	s_cbranch_scc0 .LBB0_134
	s_and_b64 vcc, exec, s[26:27]
	s_cbranch_vccz .LBB0_130

; __device__ __forceinline__ unsigned xb_ld(unsigned* p)              { return __hip_atomic_load(p, __ATOMIC_RELAXED, __HIP_MEMORY_SCOPE_AGENT); }
; __device__ __forceinline__ unsigned xb_add(unsigned* p, unsigned v) { return __hip_atomic_fetch_add(p, v, __ATOMIC_RELAXED, __HIP_MEMORY_SCOPE_AGENT); }
; #define XB_SPIN(cond, bar) do { unsigned _sp = 0; while (cond) { __builtin_amdgcn_s_sleep(1); \
;     if ((++_sp & 255u) == 0u) { if (xb_ld(&(bar)[XB_TMO])) break; if (_sp > XB_SPIN_CAP) { atomicAdd(&(bar)[XB_TMO], 1u); break; } } } } while (0)
; __device__ __forceinline__ void xcd_barrier(const XcdBarrier& b) {
;     ...
;             else XB_SPIN(xb_ld(&bar[XB_TOPGEN]) == tg, bar);
;             __builtin_amdgcn_fence(__ATOMIC_ACQUIRE, "agent");
;             xb_add(&bar[XB_XGEN(b.x)], 1u);
;             asm volatile("s_waitcnt vmcnt(0)" ::: "memory");
;         } else {
;             XB_SPIN(xb_ld(&bar[XB_XGEN(b.x)]) == gen, bar);
.LBB0_992:
	s_and_b32 s28, s33, 0xff
	s_mov_b64 s[26:27], -1
	s_cmp_lg_u32 s28, 0
	s_mov_b64 s[30:31], -1
	s_sleep 6
	s_cbranch_scc0 .LBB0_995
	s_and_b64 vcc, exec, s[30:31]
	s_cbranch_vccz .LBB0_991

; __device__ __forceinline__ unsigned xb_ld(unsigned* p)              { return __hip_atomic_load(p, __ATOMIC_RELAXED, __HIP_MEMORY_SCOPE_AGENT); }
; __device__ __forceinline__ unsigned xb_add(unsigned* p, unsigned v) { return __hip_atomic_fetch_add(p, v, __ATOMIC_RELAXED, __HIP_MEMORY_SCOPE_AGENT); }
; #define XB_SPIN(cond, bar) do { unsigned _sp = 0; while (cond) { __builtin_amdgcn_s_sleep(1); \
;     if ((++_sp & 255u) == 0u) { if (xb_ld(&(bar)[XB_TMO])) break; if (_sp > XB_SPIN_CAP) { atomicAdd(&(bar)[XB_TMO], 1u); break; } } } } while (0)
; __device__ __forceinline__ void xcd_barrier(const XcdBarrier& b) {
;     ...
;             else XB_SPIN(xb_ld(&bar[XB_TOPGEN]) == tg, bar);
;             __builtin_amdgcn_fence(__ATOMIC_ACQUIRE, "agent");
;             xb_add(&bar[XB_XGEN(b.x)], 1u);
;             asm volatile("s_waitcnt vmcnt(0)" ::: "memory");
;         } else {
;             XB_SPIN(xb_ld(&bar[XB_XGEN(b.x)]) == gen, bar);
.LBB0_1068:
	s_and_b32 s22, s26, 0xff
	s_mov_b64 s[20:21], -1
	s_cmp_lg_u32 s22, 0
	s_mov_b64 s[24:25], -1
	s_sleep 6
	s_cbranch_scc0 .LBB0_1071
	s_and_b64 vcc, exec, s[24:25]
	s_cbranch_vccz .LBB0_1067

; __device__ __forceinline__ unsigned xb_ld(unsigned* p)              { return __hip_atomic_load(p, __ATOMIC_RELAXED, __HIP_MEMORY_SCOPE_AGENT); }
; __device__ __forceinline__ unsigned xb_add(unsigned* p, unsigned v) { return __hip_atomic_fetch_add(p, v, __ATOMIC_RELAXED, __HIP_MEMORY_SCOPE_AGENT); }
; #define XB_SPIN(cond, bar) do { unsigned _sp = 0; while (cond) { __builtin_amdgcn_s_sleep(1); \
;     if ((++_sp & 255u) == 0u) { if (xb_ld(&(bar)[XB_TMO])) break; if (_sp > XB_SPIN_CAP) { atomicAdd(&(bar)[XB_TMO], 1u); break; } } } } while (0)
; __device__ __forceinline__ void xcd_barrier_light(const XcdBarrier& b) {
;     ...
;             else XB_SPIN(xb_ld(&bar[XB_TOPGEN]) == tg, bar);
;             xb_add(&bar[XB_XGEN(b.x)], 1u);
;             asm volatile("s_waitcnt vmcnt(0)" ::: "memory");
;         } else {
;             XB_SPIN(xb_ld(&bar[XB_XGEN(b.x)]) == gen, bar);
.LBB0_1305:
	s_and_b32 s20, s24, 0xff
	s_mov_b64 s[18:19], -1
	s_cmp_lg_u32 s20, 0
	s_mov_b64 s[22:23], -1
	s_sleep 6
	s_cbranch_scc0 .LBB0_1308
	s_and_b64 vcc, exec, s[22:23]
	s_cbranch_vccz .LBB0_1304

; __device__ __forceinline__ unsigned xb_ld(unsigned* p)              { return __hip_atomic_load(p, __ATOMIC_RELAXED, __HIP_MEMORY_SCOPE_AGENT); }
; __device__ __forceinline__ unsigned xb_add(unsigned* p, unsigned v) { return __hip_atomic_fetch_add(p, v, __ATOMIC_RELAXED, __HIP_MEMORY_SCOPE_AGENT); }
; #define XB_SPIN(cond, bar) do { unsigned _sp = 0; while (cond) { __builtin_amdgcn_s_sleep(1); \
;     if ((++_sp & 255u) == 0u) { if (xb_ld(&(bar)[XB_TMO])) break; if (_sp > XB_SPIN_CAP) { atomicAdd(&(bar)[XB_TMO], 1u); break; } } } } while (0)
; __device__ __forceinline__ void xcd_barrier_light(const XcdBarrier& b) {
;     ...
;             else XB_SPIN(xb_ld(&bar[XB_TOPGEN]) == tg, bar);
;             xb_add(&bar[XB_XGEN(b.x)], 1u);
;             asm volatile("s_waitcnt vmcnt(0)" ::: "memory");
;         } else {
;             XB_SPIN(xb_ld(&bar[XB_XGEN(b.x)]) == gen, bar);
.LBB0_1567:
	s_and_b32 s18, s22, 0xff
	s_mov_b64 s[16:17], -1
	s_cmp_lg_u32 s18, 0
	s_mov_b64 s[20:21], -1
	s_sleep 6
	s_cbranch_scc0 .LBB0_1570
	s_and_b64 vcc, exec, s[20:21]
	s_cbranch_vccz .LBB0_1566
